# NSA top-k: the four importance words of a token read from LDS together and masked afterwards
# speedup vs baseline: 1.0032x; 1.0032x over previous
.LBB0_1096:
	s_lshl_b32 s6, s11, 10
	s_add_i32 s6, s10, s6
	v_mov_b32_e32 v18, 0
	v_lshl_add_u32 v22, v74, 2, s6
	v_mov_b32_e32 v19, 0
	ds_read_b32 v19, v22 offset:49152
	ds_read_b32 v18, v22 offset:49408
	ds_read_b32 v21, v22 offset:49664
	ds_read_b32 v20, v22 offset:49920
	s_waitcnt lgkmcnt(0)
	v_cndmask_b32_e64 v19, v19, v202, s[36:37]
	v_cndmask_b32_e64 v18, v18, v202, s[40:41]
	v_cndmask_b32_e64 v21, v21, v202, s[44:45]
	v_cndmask_b32_e64 v20, v20, v202, s[48:49]
	v_cndmask_b32_e64 v19, 0, v19, s[34:35]
	v_cndmask_b32_e64 v18, 0, v18, s[38:39]
	v_cndmask_b32_e64 v21, 0, v21, s[42:43]
	v_cndmask_b32_e64 v20, 0, v20, s[46:47]
	s_and_b64 vcc, exec, s[28:29]
	s_mov_b64 s[6:7], -1
	s_cbranch_vccnz .LBB0_1122
	s_mov_b64 s[52:53], 0
	s_mov_b32 s54, 0
	s_mov_b32 s55, 0x40000000

.LBB0_1116:
	s_or_b64 exec, exec, s[56:57]
	s_or_b32 s13, s11, 1
	s_lshl_b32 s6, s13, 10
	s_add_i32 s6, s10, s6
	v_mov_b32_e32 v19, 0
	v_lshl_add_u32 v23, v74, 2, s6
	v_mov_b32_e32 v20, 0
	ds_read_b32 v20, v23 offset:49152
	ds_read_b32 v19, v23 offset:49408
	ds_read_b32 v22, v23 offset:49664
	ds_read_b32 v21, v23 offset:49920
	s_waitcnt lgkmcnt(0)
	v_cndmask_b32_e64 v20, v20, v202, s[36:37]
	v_cndmask_b32_e64 v19, v19, v202, s[40:41]
	v_cndmask_b32_e64 v22, v22, v202, s[44:45]
	v_cndmask_b32_e64 v21, v21, v202, s[48:49]
	v_cndmask_b32_e64 v20, 0, v20, s[34:35]
	v_cndmask_b32_e64 v19, 0, v19, s[38:39]
	v_cndmask_b32_e64 v22, 0, v22, s[42:43]
	v_cndmask_b32_e64 v21, 0, v21, s[46:47]
	s_branch .Ltk_imp_b_done

.Ltk_imp_b_done:
	s_and_b64 vcc, exec, s[28:29]
	s_mov_b64 s[6:7], -1
	s_cbranch_vccnz .LBB0_1137
	s_mov_b64 s[52:53], 0
	s_mov_b32 s54, 0
	s_mov_b32 s55, 0x40000000
